# nine split barriers with the cache invalidate at the arrive (as the unsplit barrier did) instead of at the wait
# baseline (speedup 1.0000x reference)
.Lsl0_out:
	s_cmp_gt_i32 s88, 0
	s_cbranch_scc1 .Lsb0_skip
	s_cmp_lt_i32 s89, 2
	s_cbranch_scc1 .Lsb0_skip
	s_waitcnt vmcnt(0) lgkmcnt(0)
	s_and_saveexec_b64 s[16:17], s[92:93]
	s_cbranch_execz .Lsb0_done
	v_mov_b32_e32 v0, 0x24008
	ds_read_b32 v1, v0
	s_add_u32 s18, s34, 0xed10500
	s_addc_u32 s19, s35, 0
	v_mov_b32_e32 v0, 0
	s_mov_b32 s20, 0
	s_waitcnt lgkmcnt(0)

.Lsl1_out:
	s_cmp_gt_i32 s88, 1
	s_cbranch_scc1 .Lsb1_skip
	s_cmp_lt_i32 s89, 3
	s_cbranch_scc1 .Lsb1_skip
	s_waitcnt vmcnt(0) lgkmcnt(0)
	s_and_saveexec_b64 s[16:17], s[92:93]
	s_cbranch_execz .Lsb1_done
	v_mov_b32_e32 v0, 0x24008
	ds_read_b32 v1, v0
	s_add_u32 s18, s34, 0xed10500
	s_addc_u32 s19, s35, 0
	v_mov_b32_e32 v0, 0
	s_mov_b32 s20, 0
	s_waitcnt lgkmcnt(0)

.Lsl2_out:
	s_cmp_gt_i32 s88, 2
	s_cbranch_scc1 .Lsb2_skip
	s_cmp_lt_i32 s89, 4
	s_cbranch_scc1 .Lsb2_skip
	s_waitcnt vmcnt(0) lgkmcnt(0)
	s_and_saveexec_b64 s[16:17], s[92:93]
	s_cbranch_execz .Lsb2_done
	v_mov_b32_e32 v0, 0x24008
	ds_read_b32 v1, v0
	s_add_u32 s18, s34, 0xed10500
	s_addc_u32 s19, s35, 0
	v_mov_b32_e32 v0, 0
	s_mov_b32 s20, 0
	s_waitcnt lgkmcnt(0)

.Lsl3_out:
	s_cmp_gt_i32 s88, 3
	s_cbranch_scc1 .Lsb3_skip
	s_cmp_lt_i32 s89, 5
	s_cbranch_scc1 .Lsb3_skip
	s_waitcnt vmcnt(0) lgkmcnt(0)
	s_and_saveexec_b64 s[16:17], s[92:93]
	s_cbranch_execz .Lsb3_done
	v_mov_b32_e32 v0, 0x24008
	ds_read_b32 v1, v0
	s_add_u32 s18, s34, 0xed10500
	s_addc_u32 s19, s35, 0
	v_mov_b32_e32 v0, 0
	s_mov_b32 s20, 0
	s_waitcnt lgkmcnt(0)

.Lsl4_out:
	s_cmp_gt_i32 s88, 4
	s_cbranch_scc1 .Lsb4_skip
	s_cmp_lt_i32 s89, 6
	s_cbranch_scc1 .Lsb4_skip
	s_waitcnt vmcnt(0) lgkmcnt(0)
	s_and_saveexec_b64 s[16:17], s[92:93]
	s_cbranch_execz .Lsb4_done
	v_mov_b32_e32 v0, 0x24008
	ds_read_b32 v1, v0
	s_add_u32 s18, s34, 0xed10500
	s_addc_u32 s19, s35, 0
	v_mov_b32_e32 v0, 0
	s_mov_b32 s20, 0
	s_waitcnt lgkmcnt(0)

.Lsl6_out:
	s_cmp_gt_i32 s88, 6
	s_cbranch_scc1 .Lsb6_skip
	s_cmp_lt_i32 s89, 8
	s_cbranch_scc1 .Lsb6_skip
	s_waitcnt vmcnt(0) lgkmcnt(0)
	s_and_saveexec_b64 s[16:17], s[92:93]
	s_cbranch_execz .Lsb6_done
	v_mov_b32_e32 v0, 0x24008
	ds_read_b32 v1, v0
	s_add_u32 s18, s34, 0xed10500
	s_addc_u32 s19, s35, 0
	v_mov_b32_e32 v0, 0
	s_mov_b32 s20, 0
	s_waitcnt lgkmcnt(0)

.Lsl7_out:
	s_cmp_gt_i32 s88, 7
	s_cbranch_scc1 .Lsb7_skip
	s_cmp_lt_i32 s89, 9
	s_cbranch_scc1 .Lsb7_skip
	s_waitcnt vmcnt(0) lgkmcnt(0)
	s_and_saveexec_b64 s[16:17], s[92:93]
	s_cbranch_execz .Lsb7_done
	v_mov_b32_e32 v0, 0x24008
	ds_read_b32 v1, v0
	s_add_u32 s18, s34, 0xed10500
	s_addc_u32 s19, s35, 0
	v_mov_b32_e32 v0, 0
	s_mov_b32 s20, 0
	s_waitcnt lgkmcnt(0)

.Lsl8_out:
	s_cmp_gt_i32 s88, 8
	s_cbranch_scc1 .Lsb8_skip
	s_cmp_lt_i32 s89, 10
	s_cbranch_scc1 .Lsb8_skip
	s_waitcnt vmcnt(0) lgkmcnt(0)
	s_and_saveexec_b64 s[16:17], s[92:93]
	s_cbranch_execz .Lsb8_done
	v_mov_b32_e32 v0, 0x24008
	ds_read_b32 v1, v0
	s_add_u32 s18, s34, 0xed10500
	s_addc_u32 s19, s35, 0
	v_mov_b32_e32 v0, 0
	s_mov_b32 s20, 0
	s_waitcnt lgkmcnt(0)

.Lsl9_out:
	s_cmp_gt_i32 s88, 9
	s_cbranch_scc1 .Lsb9_skip
	s_cmp_lt_i32 s89, 11
	s_cbranch_scc1 .Lsb9_skip
	s_waitcnt vmcnt(0) lgkmcnt(0)
	s_and_saveexec_b64 s[16:17], s[92:93]
	s_cbranch_execz .Lsb9_done
	v_mov_b32_e32 v0, 0x24008
	ds_read_b32 v1, v0
	s_add_u32 s18, s34, 0xed10500
	s_addc_u32 s19, s35, 0
	v_mov_b32_e32 v0, 0
	s_mov_b32 s20, 0
	s_waitcnt lgkmcnt(0)
